# v39 + latent-only rmsnorm+mod loop at LBB0_1827: gain loads hoisted out of the row loop, 12 per-row loads issued together, counted vmcnt
# baseline (speedup 1.0000x reference)
; __device__ __forceinline__ int otid() { int t = threadIdx.x; asm volatile("" : "+v"(t)); return t; }
;     const int tid_ = otid(); const int lane = tid_ & 63, w = tid_ >> 6;
;     if (bidx < 0) { bidx = blockIdx.x; nblk = gridDim.x; }
;     const int gw = bidx * 8 + w, nw = nblk * 8;
;     for (int r = rbeg + gw; r < nrows; r += nw) {
;         const float* xp = (r < T_LAT) ? xlat + (size_t)r * DM : xctx + (size_t)(r - T_LAT) * DM;
;         const int m = (r < T_LAT) ? (r >> 12) : 8;
;         const float* mv = p.modv + ((size_t)layer * 9 + m) * 6144 + shift_i * 1024;
;         f32x4 v[4];
;         float ss = 0.f;
; #pragma unroll
;         for (int i = 0; i < 4; ++i) {
;             v[i] = *reinterpret_cast<const f32x4*>(xp + (i * 64 + lane) * 4);
;             ss += v[i][0] * v[i][0] + v[i][1] * v[i][1] + v[i][2] * v[i][2] + v[i][3] * v[i][3];
;         }
; #pragma unroll
;         for (int o = 32; o >= 1; o >>= 1) ss += __shfl_xor(ss, o);
;         const float rstd = rsqrtf(ss * (1.0f / 1024.0f) + EPSV);
;         bf16_t* hp = p.hbuf + (size_t)r * DM;
; #pragma unroll
;         for (int i = 0; i < 4; ++i) {
;             const int col = (i * 64 + lane) * 4;
;             f32x4 gg = *reinterpret_cast<const f32x4*>(g + col);
.LBB0_1825:
	v_mov_b32_e32 v2, v176
	v_readlane_b32 s0, v253, 42
	v_ashrrev_i32_e32 v1, 6, v2
	s_nop 0
	v_add_u32_e32 v22, s0, v1
	s_mov_b32 s0, 0x8000
	v_cmp_gt_i32_e32 vcc, s0, v22
	s_and_saveexec_b64 s[10:11], vcc
	v_readlane_b32 s64, v254, 6
	v_readlane_b32 s70, v254, 12
	v_readlane_b32 s71, v254, 13
	v_readlane_b32 s65, v254, 7
	v_readlane_b32 s66, v254, 8
	v_readlane_b32 s67, v254, 9
	v_readlane_b32 s68, v254, 10
	v_readlane_b32 s69, v254, 11
	s_cbranch_execz .LBB0_1828
	v_lshlrev_b32_e32 v1, 2, v2
	v_cmp_lt_i32_e32 vcc, v183, v182
	v_and_b32_e32 v4, 0xfc, v1
	v_ashrrev_i32_e32 v23, 31, v22
	v_cndmask_b32_e32 v1, v180, v183, vcc
	v_cmp_lt_i32_e32 vcc, v184, v182
	v_lshlrev_b64 v[12:13], 12, v[22:23]
	v_and_b32_e32 v5, 63, v2
	v_cndmask_b32_e32 v3, v180, v184, vcc
	v_cmp_lt_i32_e32 vcc, v185, v182
	v_lshlrev_b32_e32 v39, 2, v3
	v_readlane_b32 s0, v254, 14
	v_cndmask_b32_e32 v3, v180, v185, vcc
	v_cmp_lt_i32_e32 vcc, v186, v182
	v_lshlrev_b32_e32 v44, 2, v3
	v_lshl_or_b32 v12, v5, 4, v12
	v_cndmask_b32_e32 v3, v180, v186, vcc
	v_cmp_lt_i32_e32 vcc, v187, v182
	v_lshlrev_b32_e32 v45, 2, v3
	v_readlane_b32 s1, v254, 15
	v_cndmask_b32_e32 v3, v180, v187, vcc
	v_cmp_lt_i32_e32 vcc, v188, v182
	v_lshlrev_b32_e32 v46, 2, v3
	v_lshlrev_b32_e32 v6, 2, v4
	v_cndmask_b32_e32 v3, v180, v188, vcc
	v_mov_b32_e32 v7, v0
	v_lshlrev_b32_e32 v47, 2, v3
	v_lshl_add_u64 v[26:27], s[0:1], 0, v[12:13]
	v_lshlrev_b64 v[2:3], 11, v[22:23]
	v_readlane_b32 s0, v254, 20
	v_lshl_add_u64 v[24:25], s[46:47], 0, v[6:7]
	v_or_b32_e32 v6, 0x100, v4
	v_or_b32_e32 v8, 0x200, v4
	v_or_b32_e32 v10, 0x300, v4
	v_lshl_or_b32 v2, v5, 3, v2
	v_readlane_b32 s1, v254, 21
	s_mul_i32 s20, s5, 9
	v_lshlrev_b32_e32 v1, 2, v1
	v_lshl_add_u64 v[28:29], s[0:1], 0, v[2:3]
	s_mov_b64 s[12:13], 0
	v_lshlrev_b32_e32 v30, 2, v4
	v_lshlrev_b32_e32 v32, 2, v6
	v_lshlrev_b32_e32 v34, 2, v8
	v_lshlrev_b32_e32 v36, 2, v10
	global_load_dwordx4 v[200:203], v[24:25], off
	global_load_dwordx4 v[204:207], v[24:25], off offset:1024
	global_load_dwordx4 v[208:211], v[24:25], off offset:2048
	global_load_dwordx4 v[212:215], v[24:25], off offset:3072
;     ...
;     for (int r = rbeg + gw; r < nrows; r += nw) {
;         const float* xp = (r < T_LAT) ? xlat + (size_t)r * DM : xctx + (size_t)(r - T_LAT) * DM;
;         const int m = (r < T_LAT) ? (r >> 12) : 8;
;         const float* mv = p.modv + ((size_t)layer * 9 + m) * 6144 + shift_i * 1024;
;         f32x4 v[4];
;         float ss = 0.f;
; #pragma unroll
;         for (int i = 0; i < 4; ++i) {
;             v[i] = *reinterpret_cast<const f32x4*>(xp + (i * 64 + lane) * 4);
;             ss += v[i][0] * v[i][0] + v[i][1] * v[i][1] + v[i][2] * v[i][2] + v[i][3] * v[i][3];
;         }
; #pragma unroll
;         for (int o = 32; o >= 1; o >>= 1) ss += __shfl_xor(ss, o);
;         const float rstd = rsqrtf(ss * (1.0f / 1024.0f) + EPSV);
;         bf16_t* hp = p.hbuf + (size_t)r * DM;
; #pragma unroll
;         for (int i = 0; i < 4; ++i) {
;             const int col = (i * 64 + lane) * 4;
;             f32x4 gg = *reinterpret_cast<const f32x4*>(g + col);
;             f32x4 sh = *reinterpret_cast<const f32x4*>(mv + col);
;             f32x4 sc = *reinterpret_cast<const f32x4*>(mv + 1024 + col);
;             float o0 = v[i][0] * rstd * gg[0] * (1.f + sc[0]) + sh[0];
;             float o1 = v[i][1] * rstd * gg[1] * (1.f + sc[1]) + sh[1];
;             float o2 = v[i][2] * rstd * gg[2] * (1.f + sc[2]) + sh[2];
;             float o3 = v[i][3] * rstd * gg[3] * (1.f + sc[3]) + sh[3];
;             u32x2 o = {pack2(o0, o1), pack2(o2, o3)};
;             *reinterpret_cast<u32x2*>(hp + col) = o;
;         }
;     }
.LBB0_1827:
	global_load_dwordx4 v[14:17], v[26:27], off offset:-2048
	global_load_dwordx4 v[10:13], v[26:27], off offset:-1024
	global_load_dwordx4 v[192:195], v[26:27], off
	global_load_dwordx4 v[196:199], v[26:27], off offset:1024
	v_ashrrev_i32_e32 v2, 12, v22
	v_ashrrev_i32_e32 v3, 31, v2
	v_lshl_add_u64 v[2:3], v[2:3], 0, s[20:21]
	v_mov_b64_e32 v[4:5], s[70:71]
	v_mad_u64_u32 v[18:19], s[0:1], v2, s74, v[4:5]
	v_mad_i32_i24 v19, v3, s74, v19
	v_mov_b32_e32 v31, v0
	v_mov_b32_e32 v33, v0
	v_mov_b32_e32 v35, v0
	v_mov_b32_e32 v37, v0
	v_lshl_add_u64 v[240:241], v[18:19], 0, v[30:31]
	v_lshl_add_u64 v[248:249], v[18:19], 0, s[90:91]
	global_load_dwordx4 v[216:219], v[240:241], off
	global_load_dwordx4 v[220:223], v[240:241], off offset:1024
	global_load_dwordx4 v[224:227], v[240:241], off offset:2048
	global_load_dwordx4 v[228:231], v[240:241], off offset:3072
	v_lshl_add_u64 v[240:241], v[248:249], 0, v[30:31]
	global_load_dwordx4 v[52:55], v[240:241], off
	v_lshl_add_u64 v[240:241], v[248:249], 0, v[32:33]
	global_load_dwordx4 v[232:235], v[240:241], off
	v_lshl_add_u64 v[240:241], v[248:249], 0, v[34:35]
	global_load_dwordx4 v[236:239], v[240:241], off
	v_lshl_add_u64 v[240:241], v[248:249], 0, v[36:37]
	global_load_dwordx4 v[244:247], v[240:241], off
	v_add_u32_e32 v22, s18, v22
	v_lshl_add_u64 v[26:27], v[26:27], 0, s[22:23]
	s_waitcnt vmcnt(10)
	v_mov_b32_e32 v4, v15
	v_mov_b32_e32 v5, v11
	v_mov_b32_e32 v2, v14
	v_mov_b32_e32 v3, v10
	v_pk_mul_f32 v[4:5], v[4:5], v[4:5]
	s_nop 0
	v_pk_fma_f32 v[2:3], v[2:3], v[2:3], v[4:5]
	v_mov_b32_e32 v4, v16
	v_mov_b32_e32 v5, v12
	v_pk_fma_f32 v[2:3], v[4:5], v[4:5], v[2:3]
	v_mov_b32_e32 v4, v17
	v_mov_b32_e32 v5, v13
	v_pk_fma_f32 v[20:21], v[4:5], v[4:5], v[2:3]
	s_waitcnt vmcnt(8)
	v_mov_b32_e32 v6, v192
	v_mov_b32_e32 v7, v193
	v_mov_b32_e32 v8, v194
	v_mov_b32_e32 v9, v195
	v_mov_b32_e32 v2, v196
	v_mov_b32_e32 v3, v197
	v_mov_b32_e32 v4, v198
	v_mov_b32_e32 v5, v199
	v_add_f32_e32 v20, v20, v21
	v_mov_b32_e32 v42, v7
	v_mov_b32_e32 v43, v3
	v_mov_b32_e32 v40, v6
	v_mov_b32_e32 v41, v2
	v_pk_mul_f32 v[42:43], v[42:43], v[42:43]
	s_nop 0
	v_pk_fma_f32 v[40:41], v[40:41], v[40:41], v[42:43]
	v_mov_b32_e32 v42, v8
	v_mov_b32_e32 v43, v4
	v_pk_fma_f32 v[40:41], v[42:43], v[42:43], v[40:41]
	v_mov_b32_e32 v42, v9
	v_mov_b32_e32 v43, v5
	v_pk_fma_f32 v[40:41], v[42:43], v[42:43], v[40:41]
	s_nop 0
	v_add_f32_e32 v20, v20, v40
	v_add_f32_e32 v20, v20, v41
	ds_bpermute_b32 v21, v1, v20
	s_waitcnt lgkmcnt(0)
	v_add_f32_e32 v20, v20, v21
	ds_bpermute_b32 v21, v39, v20
	s_waitcnt lgkmcnt(0)
	v_add_f32_e32 v20, v20, v21
	ds_bpermute_b32 v21, v44, v20
	s_waitcnt lgkmcnt(0)
	v_add_f32_e32 v20, v20, v21
	ds_bpermute_b32 v21, v45, v20
	s_waitcnt lgkmcnt(0)
	v_add_f32_e32 v20, v20, v21
	ds_bpermute_b32 v21, v46, v20
	s_waitcnt lgkmcnt(0)
	v_add_f32_e32 v20, v20, v21
	ds_bpermute_b32 v21, v47, v20
	s_waitcnt lgkmcnt(0)
	v_add_f32_e32 v20, v20, v21
	v_fmamk_f32 v20, v20, 0x3a800000, v177
	v_cmp_gt_f32_e32 vcc, s93, v20
	v_mul_f32_e32 v21, 0x4b800000, v20
	s_nop 0
	v_cndmask_b32_e32 v20, v20, v21, vcc
	v_rsq_f32_e32 v20, v20
	s_nop 0
	v_mul_f32_e32 v21, 0x45800000, v20
	v_cndmask_b32_e32 v38, v20, v21, vcc
	v_pk_mul_f32 v[14:15], v[14:15], v[38:39] op_sel_hi:[1,0]
	v_pk_mul_f32 v[16:17], v[16:17], v[38:39] op_sel_hi:[1,0]
	v_pk_mul_f32 v[10:11], v[10:11], v[38:39] op_sel_hi:[1,0]
	v_pk_mul_f32 v[12:13], v[12:13], v[38:39] op_sel_hi:[1,0]
	v_pk_mul_f32 v[6:7], v[6:7], v[38:39] op_sel_hi:[1,0]
	v_pk_mul_f32 v[8:9], v[8:9], v[38:39] op_sel_hi:[1,0]
	v_pk_mul_f32 v[2:3], v[2:3], v[38:39] op_sel_hi:[1,0]
	v_pk_mul_f32 v[4:5], v[4:5], v[38:39] op_sel_hi:[1,0]
	v_cmp_lt_i32_e32 vcc, s72, v22
	s_or_b64 s[12:13], vcc, s[12:13]
	s_waitcnt vmcnt(0)
	v_pk_mul_f32 v[14:15], v[200:201], v[14:15]
	v_pk_mul_f32 v[16:17], v[202:203], v[16:17]
	v_pk_add_f32 v[48:49], v[52:53], 1.0 op_sel_hi:[1,0]
	s_nop 0
	v_pk_fma_f32 v[14:15], v[48:49], v[14:15], v[216:217]
	v_pk_add_f32 v[18:19], v[54:55], 1.0 op_sel_hi:[1,0]
	v_cvt_pk_bf16_f32 v14, v14, v15
	v_pk_fma_f32 v[16:17], v[18:19], v[16:17], v[218:219]
	v_pk_mul_f32 v[10:11], v[204:205], v[10:11]
	v_cvt_pk_bf16_f32 v15, v16, v17
	global_store_dwordx2 v[28:29], v[14:15], off offset:-1024
	v_pk_mul_f32 v[12:13], v[206:207], v[12:13]
	v_pk_add_f32 v[18:19], v[232:233], 1.0 op_sel_hi:[1,0]
	s_nop 0
	v_pk_fma_f32 v[10:11], v[18:19], v[10:11], v[220:221]
	v_pk_add_f32 v[14:15], v[234:235], 1.0 op_sel_hi:[1,0]
	v_cvt_pk_bf16_f32 v10, v10, v11
	v_pk_fma_f32 v[12:13], v[14:15], v[12:13], v[222:223]
	v_pk_mul_f32 v[6:7], v[208:209], v[6:7]
	v_cvt_pk_bf16_f32 v11, v12, v13
	global_store_dwordx2 v[28:29], v[10:11], off offset:-512
	v_pk_mul_f32 v[8:9], v[210:211], v[8:9]
	v_pk_add_f32 v[10:11], v[236:237], 1.0 op_sel_hi:[1,0]
	s_nop 0
	v_pk_fma_f32 v[6:7], v[10:11], v[6:7], v[224:225]
	v_pk_add_f32 v[10:11], v[238:239], 1.0 op_sel_hi:[1,0]
	v_cvt_pk_bf16_f32 v6, v6, v7
	v_pk_fma_f32 v[8:9], v[10:11], v[8:9], v[226:227]
	v_pk_mul_f32 v[2:3], v[2:3], v[212:213]
	v_cvt_pk_bf16_f32 v7, v8, v9
	global_store_dwordx2 v[28:29], v[6:7], off
	v_pk_mul_f32 v[4:5], v[4:5], v[214:215]
	v_pk_add_f32 v[6:7], v[244:245], 1.0 op_sel_hi:[1,0]
	s_nop 0
	v_pk_fma_f32 v[2:3], v[2:3], v[6:7], v[228:229]
	v_pk_add_f32 v[6:7], v[246:247], 1.0 op_sel_hi:[1,0]
	v_cvt_pk_bf16_f32 v2, v2, v3
	v_pk_fma_f32 v[4:5], v[4:5], v[6:7], v[230:231]
	s_nop 0
	v_cvt_pk_bf16_f32 v3, v4, v5
	global_store_dwordx2 v[28:29], v[2:3], off offset:512
	v_lshl_add_u64 v[28:29], v[28:29], 0, s[28:29]
	s_andn2_b64 exec, exec, s[12:13]
	s_cbranch_execnz .LBB0_1827
